# plus: final RMSNorm and MLP-norm row loops issue all 8 row loads before the first wait (compiler had split them into 3 and 5 serialized batches)
# speedup vs baseline: 1.0127x; 1.0067x over previous
; __device__ __forceinline__ unsigned cvt_pk_bf16(float lo, float hi) { f32x2 v = {lo, hi}; bf16x2_t r = __builtin_convertvector(v, bf16x2_t); return __builtin_bit_cast(unsigned, r); }
; __device__ __forceinline__ void phase_g(KA a, int layer, const float* x1, unsigned char* lds, const int tid_, const int bid_) {
;     ...
;     for (int m = gw; m < T_; m += NGW) {
;         const f32x4* xr = (const f32x4*)(x1 + (size_t)m * D_) + lane;
;         f32x4 v[8]; float ss = 0.f;
; #pragma unroll
;         for (int j = 0; j < 8; ++j) { v[j] = xr[64 * j]; ss += (v[j].x * v[j].x + v[j].y * v[j].y) + (v[j].z * v[j].z + v[j].w * v[j].w); }
;         ss = wave_sum(ss);
;         const float rstd = rsqrtf(ss * (1.0f / D_) + 1e-6f);
;         u32x2* o8 = (u32x2*)(H + (size_t)m * D_) + lane;
; #pragma unroll
;         for (int j = 0; j < 8; ++j) { v[j] = v[j] * rstd * gn[j]; u32x2 w; w.x = cvt_pk_bf16(v[j].x, v[j].y); w.y = cvt_pk_bf16(v[j].z, v[j].w); o8[64 * j] = w; }
;     }
.LBB0_50:
	global_load_dwordx4 v[38:41], v[44:45], off offset:-4096
	global_load_dwordx4 v[34:37], v[44:45], off offset:-3072
	global_load_dwordx4 v[56:59], v[44:45], off offset:-2048
	global_load_dwordx4 v[60:63], v[44:45], off offset:-1024
	global_load_dwordx4 v[64:67], v[44:45], off
	global_load_dwordx4 v[68:71], v[44:45], off offset:1024
	global_load_dwordx4 v[72:75], v[44:45], off offset:2048
	global_load_dwordx4 v[76:79], v[44:45], off offset:3072
	v_add_u32_e32 v42, s8, v42
	s_waitcnt vmcnt(6)
	v_mov_b32_e32 v158, v39
	v_mov_b32_e32 v159, v35
	v_mov_b32_e32 v156, v38
	v_mov_b32_e32 v157, v34
	v_pk_mul_f32 v[158:159], v[158:159], v[158:159]
	v_mov_b32_e32 v160, v41
	v_mov_b32_e32 v161, v37
	v_pk_fma_f32 v[156:157], v[156:157], v[156:157], v[158:159]
	v_mov_b32_e32 v158, v40
	v_mov_b32_e32 v159, v36
	v_pk_mul_f32 v[160:161], v[160:161], v[160:161]
	s_nop 0
	v_pk_fma_f32 v[158:159], v[158:159], v[158:159], v[160:161]
	s_nop 0
	v_pk_add_f32 v[168:169], v[156:157], v[158:159]
	v_pk_add_f32 v[168:169], v[168:169], v[168:169] op_sel:[0,1] op_sel_hi:[1,0]
	s_waitcnt vmcnt(5)
	v_pk_mul_f32 v[160:161], v[58:59], v[58:59]
	v_pk_mul_f32 v[162:163], v[56:57], v[56:57]
	s_nop 0
	v_pk_mov_b32 v[164:165], v[162:163], v[160:161] op_sel:[1,0]
	v_mov_b32_e32 v163, v161
	v_pk_add_f32 v[170:171], v[164:165], v[162:163]
	v_pk_add_f32 v[170:171], v[170:171], v[170:171] op_sel:[0,1] op_sel_hi:[1,0]
	s_waitcnt vmcnt(3)
	v_mul_f32_e32 v0, v64, v64
	v_mul_f32_e32 v43, v65, v65
	v_mov_b32_e32 v169, v0
	v_mov_b32_e32 v171, v43
	v_mul_f32_e32 v0, v61, v61
	v_pk_add_f32 v[168:169], v[168:169], v[170:171]
	v_pk_fma_f32 v[170:171], v[60:61], v[60:61], v[0:1] op_sel_hi:[1,1,0]
	v_mul_f32_e32 v0, v63, v63
	v_mul_f32_e32 v48, v66, v66
	v_mul_f32_e32 v55, v67, v67
	v_pk_fma_f32 v[172:173], v[62:63], v[62:63], v[0:1] op_sel_hi:[1,1,0]
	v_mov_b32_e32 v171, v48
	v_mov_b32_e32 v173, v55
	v_pk_add_f32 v[170:171], v[170:171], v[172:173]
	s_nop 0
	v_pk_add_f32 v[80:81], v[168:169], v[170:171]
	v_pk_add_f32 v[80:81], v[80:81], v[80:81] op_sel:[0,1] op_sel_hi:[1,0]
	s_waitcnt vmcnt(2)
	v_pk_mul_f32 v[172:173], v[70:71], v[70:71]
	v_pk_mul_f32 v[174:175], v[68:69], v[68:69]
	s_nop 0
	v_pk_mov_b32 v[176:177], v[174:175], v[172:173] op_sel:[1,0]
	v_mov_b32_e32 v175, v173
	v_pk_add_f32 v[82:83], v[176:177], v[174:175]
	v_pk_add_f32 v[82:83], v[82:83], v[82:83] op_sel:[0,1] op_sel_hi:[1,0]
	v_lshl_add_u64 v[44:45], v[44:45], 0, s[12:13]
	s_waitcnt vmcnt(0)
	v_mul_f32_e32 v0, v76, v76
	v_mul_f32_e32 v43, v77, v77
	v_mov_b32_e32 v81, v0
	v_mov_b32_e32 v83, v43
	v_mul_f32_e32 v0, v73, v73
	v_pk_add_f32 v[80:81], v[80:81], v[82:83]
	v_pk_fma_f32 v[82:83], v[72:73], v[72:73], v[0:1] op_sel_hi:[1,1,0]
	v_mul_f32_e32 v0, v75, v75
	v_mul_f32_e32 v48, v78, v78
	v_mul_f32_e32 v55, v79, v79
	v_pk_fma_f32 v[84:85], v[74:75], v[74:75], v[0:1] op_sel_hi:[1,1,0]
	v_mov_b32_e32 v83, v48
	v_mov_b32_e32 v85, v55
	v_pk_add_f32 v[82:83], v[82:83], v[84:85]
	s_nop 0
	v_pk_add_f32 v[80:81], v[80:81], v[82:83]
	s_nop 0
	v_add_f32_e32 v0, v80, v81
	ds_bpermute_b32 v43, v49, v0
	s_waitcnt lgkmcnt(0)
	v_add_f32_e32 v0, v0, v43
	ds_bpermute_b32 v43, v50, v0
	s_waitcnt lgkmcnt(0)
	v_add_f32_e32 v0, v0, v43
	ds_bpermute_b32 v43, v51, v0
	s_waitcnt lgkmcnt(0)
	v_add_f32_e32 v0, v0, v43
	ds_bpermute_b32 v43, v52, v0
	s_waitcnt lgkmcnt(0)
	v_add_f32_e32 v0, v0, v43
	ds_bpermute_b32 v43, v53, v0
	s_waitcnt lgkmcnt(0)
	v_add_f32_e32 v0, v0, v43
	ds_bpermute_b32 v43, v54, v0
	s_waitcnt lgkmcnt(0)
	v_add_f32_e32 v0, v0, v43
	v_fmamk_f32 v0, v0, 0x3a000000, v227
	v_cmp_gt_f32_e32 vcc, s24, v0
	v_mul_f32_e32 v43, 0x4b800000, v0
	s_nop 0
	v_cndmask_b32_e32 v0, v0, v43, vcc
	v_rsq_f32_e32 v0, v0
	s_nop 0
	v_mul_f32_e32 v43, 0x45800000, v0
	v_cndmask_b32_e32 v0, v0, v43, vcc
	v_pk_mul_f32 v[34:35], v[34:35], v[0:1] op_sel_hi:[1,0]
	v_pk_mul_f32 v[36:37], v[36:37], v[0:1] op_sel_hi:[1,0]
	v_pk_mul_f32 v[34:35], v[6:7], v[34:35]
	v_pk_mul_f32 v[36:37], v[8:9], v[36:37]
	v_cvt_pk_bf16_f32 v34, v34, v35
	v_cvt_pk_bf16_f32 v35, v36, v37
	global_store_dwordx2 v[46:47], v[34:35], off offset:-3072
	v_pk_mul_f32 v[34:35], v[56:57], v[0:1] op_sel_hi:[1,0]
	v_pk_mul_f32 v[36:37], v[58:59], v[0:1] op_sel_hi:[1,0]
	v_pk_mul_f32 v[34:35], v[10:11], v[34:35]
	v_pk_mul_f32 v[36:37], v[12:13], v[36:37]
	v_cvt_pk_bf16_f32 v34, v34, v35
	v_cvt_pk_bf16_f32 v35, v36, v37
	global_store_dwordx2 v[46:47], v[34:35], off offset:-2560
	v_pk_mul_f32 v[34:35], v[60:61], v[0:1] op_sel_hi:[1,0]
	v_pk_mul_f32 v[36:37], v[62:63], v[0:1] op_sel_hi:[1,0]
	v_pk_mul_f32 v[34:35], v[14:15], v[34:35]
	v_pk_mul_f32 v[36:37], v[16:17], v[36:37]
	v_cvt_pk_bf16_f32 v34, v34, v35
	v_cvt_pk_bf16_f32 v35, v36, v37
	global_store_dwordx2 v[46:47], v[34:35], off offset:-2048
	v_pk_mul_f32 v[34:35], v[64:65], v[0:1] op_sel_hi:[1,0]
	v_pk_mul_f32 v[36:37], v[66:67], v[0:1] op_sel_hi:[1,0]
	v_pk_mul_f32 v[34:35], v[18:19], v[34:35]
	v_pk_mul_f32 v[36:37], v[20:21], v[36:37]
	v_cvt_pk_bf16_f32 v34, v34, v35
	v_cvt_pk_bf16_f32 v35, v36, v37
	global_store_dwordx2 v[46:47], v[34:35], off offset:-1536
	v_pk_mul_f32 v[34:35], v[68:69], v[0:1] op_sel_hi:[1,0]
	v_pk_mul_f32 v[36:37], v[70:71], v[0:1] op_sel_hi:[1,0]
	v_pk_mul_f32 v[34:35], v[22:23], v[34:35]
	v_pk_mul_f32 v[36:37], v[24:25], v[36:37]
	v_cvt_pk_bf16_f32 v34, v34, v35
	v_cvt_pk_bf16_f32 v35, v36, v37
	global_store_dwordx2 v[46:47], v[34:35], off offset:-1024
	v_pk_mul_f32 v[34:35], v[72:73], v[0:1] op_sel_hi:[1,0]
	v_pk_mul_f32 v[36:37], v[74:75], v[0:1] op_sel_hi:[1,0]
	v_pk_mul_f32 v[34:35], v[26:27], v[34:35]
	v_pk_mul_f32 v[36:37], v[28:29], v[36:37]
	v_cvt_pk_bf16_f32 v34, v34, v35
	v_cvt_pk_bf16_f32 v35, v36, v37
	v_pk_mul_f32 v[38:39], v[38:39], v[0:1] op_sel_hi:[1,0]
	v_pk_mul_f32 v[40:41], v[40:41], v[0:1] op_sel_hi:[1,0]
	global_store_dwordx2 v[46:47], v[34:35], off offset:-512
	v_pk_mul_f32 v[34:35], v[76:77], v[0:1] op_sel_hi:[1,0]
	v_pk_mul_f32 v[36:37], v[78:79], v[0:1] op_sel_hi:[1,0]
	v_pk_mul_f32 v[40:41], v[4:5], v[40:41]
	v_pk_mul_f32 v[38:39], v[2:3], v[38:39]
	v_pk_mul_f32 v[36:37], v[32:33], v[36:37]
	v_pk_mul_f32 v[34:35], v[30:31], v[34:35]
	v_cvt_pk_bf16_f32 v38, v38, v39
	v_cvt_pk_bf16_f32 v39, v40, v41
	v_cvt_pk_bf16_f32 v34, v34, v35
	v_cvt_pk_bf16_f32 v35, v36, v37
	v_cmp_lt_i32_e32 vcc, s22, v42
	global_store_dwordx2 v[46:47], v[38:39], off offset:-3584
	global_store_dwordx2 v[46:47], v[34:35], off
	v_lshl_add_u64 v[46:47], v[46:47], 0, s[14:15]
	s_or_b64 s[16:17], vcc, s[16:17]
	s_andn2_b64 exec, exec, s[16:17]
	s_cbranch_execnz .LBB0_50

; __device__ __forceinline__ void phase_final(KA a, const float* x, const int tid_, const int bid_) {
;     ...
;     for (int m = gw; m < T_; m += NGW) {
;         const f32x4* xr = (const f32x4*)(x + (size_t)m * D_) + lane;
;         f32x4 v[8]; float ss = 0.f;
; #pragma unroll
;         for (int j = 0; j < 8; ++j) { v[j] = xr[64 * j]; ss += (v[j].x * v[j].x + v[j].y * v[j].y) + (v[j].z * v[j].z + v[j].w * v[j].w); }
;         ss = wave_sum(ss);
;         const float rstd = rsqrtf(ss * (1.0f / D_) + 1e-6f);
;         f32x4* o = (f32x4*)(a->out + (size_t)m * D_) + lane;
; #pragma unroll
;         for (int j = 0; j < 8; ++j) o[64 * j] = v[j] * rstd * gn[j];
;     }
.LBB0_440:
	global_load_dwordx4 v[34:37], v[66:67], off offset:-2048
	global_load_dwordx4 v[38:41], v[66:67], off
	global_load_dwordx4 v[42:45], v[66:67], off offset:-1024
	v_add_co_u32_e32 v68, vcc, 0xfffff000, v66
	v_add_u32_e32 v72, s2, v72
	s_nop 0
	v_addc_co_u32_e32 v69, vcc, -1, v67, vcc
	global_load_dwordx4 v[50:53], v[68:69], off offset:-1024
	global_load_dwordx4 v[46:49], v[66:67], off offset:-4096
	global_load_dwordx4 v[58:61], v[68:69], off offset:-3072
	global_load_dwordx4 v[54:57], v[68:69], off offset:-2048
	global_load_dwordx4 v[62:65], v[66:67], off offset:-3072
	s_waitcnt vmcnt(3)
	v_pk_mul_f32 v[100:101], v[36:37], v[36:37]
	v_pk_mul_f32 v[102:103], v[34:35], v[34:35]
	v_mul_f32_e32 v0, v43, v43
	v_mul_f32_e32 v104, v45, v45
	v_mul_f32_e32 v70, v40, v40
	v_mul_f32_e32 v71, v41, v41
	v_pk_mov_b32 v[106:107], v[102:103], v[100:101] op_sel:[1,0]
	v_mov_b32_e32 v103, v101
	v_pk_fma_f32 v[100:101], v[42:43], v[42:43], v[0:1] op_sel_hi:[1,1,0]
	v_pk_fma_f32 v[104:105], v[44:45], v[44:45], v[104:105] op_sel_hi:[1,1,0]
	v_mov_b32_e32 v101, v70
	v_mov_b32_e32 v105, v71
	v_pk_add_f32 v[80:81], v[106:107], v[102:103]
	v_pk_add_f32 v[70:71], v[100:101], v[104:105]
	v_pk_mul_f32 v[108:109], v[52:53], v[52:53]
	v_pk_mul_f32 v[110:111], v[50:51], v[50:51]
	v_mul_f32_e32 v0, v47, v47
	v_pk_mov_b32 v[82:83], v[110:111], v[108:109] op_sel:[1,0]
	v_mov_b32_e32 v111, v109
	v_pk_add_f32 v[82:83], v[82:83], v[110:111]
	v_pk_add_f32 v[80:81], v[80:81], v[80:81] op_sel:[0,1] op_sel_hi:[1,0]
	v_pk_add_f32 v[82:83], v[82:83], v[82:83] op_sel:[0,1] op_sel_hi:[1,0]
	v_mul_f32_e32 v81, v39, v39
	s_waitcnt vmcnt(2)
	v_mov_b32_e32 v84, v59
	s_waitcnt vmcnt(1)
	v_mov_b32_e32 v85, v55
	v_mov_b32_e32 v108, v58
	v_mov_b32_e32 v109, v54
	v_pk_mul_f32 v[84:85], v[84:85], v[84:85]
	v_mov_b32_e32 v86, v61
	v_mov_b32_e32 v87, v57
	v_pk_fma_f32 v[108:109], v[108:109], v[108:109], v[84:85]
	v_mov_b32_e32 v84, v60
	v_mov_b32_e32 v85, v56
	v_pk_mul_f32 v[86:87], v[86:87], v[86:87]
	s_nop 0
	v_pk_fma_f32 v[84:85], v[84:85], v[84:85], v[86:87]
	v_pk_fma_f32 v[86:87], v[46:47], v[46:47], v[0:1] op_sel_hi:[1,1,0]
	v_pk_add_f32 v[84:85], v[108:109], v[84:85]
	v_mul_f32_e32 v0, v49, v49
	v_pk_fma_f32 v[88:89], v[48:49], v[48:49], v[0:1] op_sel_hi:[1,1,0]
	v_pk_add_f32 v[84:85], v[84:85], v[84:85] op_sel:[0,1] op_sel_hi:[1,0]
	s_waitcnt vmcnt(0)
	v_mul_f32_e32 v87, v64, v64
	v_mul_f32_e32 v89, v65, v65
	v_mul_f32_e32 v83, v63, v63
	v_mul_f32_e32 v85, v62, v62
	v_pk_add_f32 v[86:87], v[86:87], v[88:89]
	v_pk_add_f32 v[82:83], v[84:85], v[82:83]
	s_nop 0
	v_pk_add_f32 v[82:83], v[82:83], v[86:87]
	s_nop 0
	v_pk_add_f32 v[82:83], v[82:83], v[82:83] op_sel:[0,1] op_sel_hi:[1,0]
	s_nop 0
	v_mul_f32_e32 v83, v38, v38
	v_pk_add_f32 v[80:81], v[82:83], v[80:81]
	s_nop 0
	v_pk_add_f32 v[70:71], v[80:81], v[70:71]
	s_nop 0
	v_add_f32_e32 v0, v70, v71
	ds_bpermute_b32 v70, v73, v0
	s_waitcnt lgkmcnt(0)
	v_add_f32_e32 v0, v0, v70
	ds_bpermute_b32 v70, v74, v0
	s_waitcnt lgkmcnt(0)
	v_add_f32_e32 v0, v0, v70
	ds_bpermute_b32 v70, v75, v0
	s_waitcnt lgkmcnt(0)
	v_add_f32_e32 v0, v0, v70
	ds_bpermute_b32 v70, v76, v0
	s_waitcnt lgkmcnt(0)
	v_add_f32_e32 v0, v0, v70
	ds_bpermute_b32 v70, v77, v0
	s_waitcnt lgkmcnt(0)
	v_add_f32_e32 v0, v0, v70
	ds_bpermute_b32 v70, v78, v0
	s_waitcnt lgkmcnt(0)
	v_add_f32_e32 v0, v0, v70
	v_fmamk_f32 v0, v0, 0x3a000000, v227
	v_mul_f32_e32 v70, 0x4b800000, v0
	v_cmp_gt_f32_e32 vcc, s24, v0
	s_nop 1
	v_cndmask_b32_e32 v0, v0, v70, vcc
	v_rsq_f32_e32 v0, v0
	s_nop 0
	v_mul_f32_e32 v70, 0x45800000, v0
	v_cndmask_b32_e32 v0, v0, v70, vcc
	v_pk_mul_f32 v[58:59], v[58:59], v[0:1] op_sel_hi:[1,0]
	v_pk_mul_f32 v[60:61], v[60:61], v[0:1] op_sel_hi:[1,0]
	v_pk_mul_f32 v[54:55], v[54:55], v[0:1] op_sel_hi:[1,0]
	v_pk_mul_f32 v[56:57], v[56:57], v[0:1] op_sel_hi:[1,0]
	v_pk_mul_f32 v[50:51], v[50:51], v[0:1] op_sel_hi:[1,0]
	v_pk_mul_f32 v[52:53], v[52:53], v[0:1] op_sel_hi:[1,0]
	v_pk_mul_f32 v[46:47], v[46:47], v[0:1] op_sel_hi:[1,0]
	v_pk_mul_f32 v[48:49], v[48:49], v[0:1] op_sel_hi:[1,0]
	v_pk_mul_f32 v[62:63], v[62:63], v[0:1] op_sel_hi:[1,0]
	v_pk_mul_f32 v[64:65], v[64:65], v[0:1] op_sel_hi:[1,0]
	v_pk_mul_f32 v[70:71], v[34:35], v[0:1] op_sel_hi:[1,0]
	v_pk_mul_f32 v[80:81], v[36:37], v[0:1] op_sel_hi:[1,0]
	v_pk_mul_f32 v[82:83], v[42:43], v[0:1] op_sel_hi:[1,0]
	v_pk_mul_f32 v[84:85], v[44:45], v[0:1] op_sel_hi:[1,0]
	v_pk_mul_f32 v[86:87], v[38:39], v[0:1] op_sel_hi:[1,0]
	v_pk_mul_f32 v[88:89], v[40:41], v[0:1] op_sel_hi:[1,0]
	v_pk_mul_f32 v[36:37], v[4:5], v[60:61]
	v_pk_mul_f32 v[34:35], v[2:3], v[58:59]
	v_cmp_lt_i32_e32 vcc, s22, v72
	v_pk_mul_f32 v[40:41], v[8:9], v[56:57]
	v_pk_mul_f32 v[38:39], v[6:7], v[54:55]
	v_pk_mul_f32 v[44:45], v[12:13], v[52:53]
	v_pk_mul_f32 v[42:43], v[10:11], v[50:51]
	v_pk_mul_f32 v[48:49], v[16:17], v[48:49]
	v_pk_mul_f32 v[46:47], v[14:15], v[46:47]
	v_pk_mul_f32 v[52:53], v[20:21], v[64:65]
	v_pk_mul_f32 v[50:51], v[18:19], v[62:63]
	v_pk_mul_f32 v[56:57], v[24:25], v[80:81]
	v_pk_mul_f32 v[54:55], v[22:23], v[70:71]
	v_pk_mul_f32 v[60:61], v[28:29], v[84:85]
	v_pk_mul_f32 v[58:59], v[26:27], v[82:83]
	v_pk_mul_f32 v[64:65], v[32:33], v[88:89]
	v_pk_mul_f32 v[62:63], v[30:31], v[86:87]
	s_or_b64 s[8:9], vcc, s[8:9]
	global_store_dwordx4 v[68:69], v[34:37], off offset:-3072
	global_store_dwordx4 v[68:69], v[38:41], off offset:-2048
	global_store_dwordx4 v[68:69], v[42:45], off offset:-1024
	global_store_dwordx4 v[66:67], v[46:49], off offset:-4096
	global_store_dwordx4 v[66:67], v[50:53], off offset:-3072
	global_store_dwordx4 v[66:67], v[54:57], off offset:-2048
	global_store_dwordx4 v[66:67], v[58:61], off offset:-1024
	global_store_dwordx4 v[66:67], v[62:65], off
	v_lshl_add_u64 v[66:67], v[66:67], 0, s[6:7]
	s_andn2_b64 exec, exec, s[8:9]
	s_cbranch_execnz .LBB0_440
